# W2in conversion moved from the prologue into the FFN1-in idle slot and W2out into the Z idle slot of the same layer (conv_set masks)
# speedup vs baseline: 1.0033x; 1.0033x over previous
.LBB0_414:
	s_lshl_b32 s0, 1, s24
	s_and_b32 s0, s0, 0x206
	s_cmp_eq_u32 s0, 0
	s_cbranch_scc1 .LBB0_413
	s_mov_b32 s0, s33
	s_mov_b64 s[16:17], -1
	v_mov_b32_e32 v0, s0
	ds_read2_b32 v[2:3], v0 offset1:1
	s_waitcnt lgkmcnt(0)
	v_readfirstlane_b32 s0, v2
	v_readfirstlane_b32 s1, v3
	s_add_u32 s0, s0, s54
	s_addc_u32 s1, s1, 0
	s_add_u32 s14, s0, 0x100000
	s_addc_u32 s15, s1, 0
	s_cmp_lt_i32 s24, 2
	s_cbranch_scc1 .LBB0_440
	s_cmp_lt_i32 s24, 3
	s_cbranch_scc1 .LBB0_437
	s_cmp_lg_u32 s24, 3
	s_cbranch_scc0 .LBB0_434
	s_cmp_gt_u32 s24, 7
	s_cbranch_scc0 .LBB0_431
	s_cmp_lt_i32 s24, 9
	s_cbranch_scc1 .LBB0_428
	s_cmp_lt_i32 s24, 10
	s_mov_b64 s[10:11], -1
	s_cbranch_scc1 .LBB0_426
	s_cmp_lg_u32 s24, 10
	s_mov_b64 s[8:9], -1
	s_cbranch_scc0 .LBB0_423
	v_readlane_b32 s0, v254, 0
	s_add_i32 s94, s24, -11
	s_mov_b64 s[8:9], 0
	v_mov_b32_e32 v0, s0
	ds_read2_b32 v[2:3], v0 offset1:1
	s_waitcnt lgkmcnt(0)
	v_readfirstlane_b32 s0, v2
	v_readfirstlane_b32 s1, v3
	s_add_u32 s6, s0, s4
	s_addc_u32 s7, s1, s5
	s_lshl_b64 s[0:1], s[94:95], 21
	s_add_u32 s6, s6, s0
	s_addc_u32 s7, s7, s1
	s_lshl_b64 s[0:1], s[94:95], 20
	s_add_u32 s0, s14, s0
	s_addc_u32 s1, s15, s1
	s_add_u32 s0, s0, 0x3280000
	s_addc_u32 s1, s1, 0

.LBB0_1152:
	s_lshl_b32 s0, 1, s24
	s_and_b32 s0, s0, 0x1df0
	s_cmp_eq_u32 s0, 0
	s_cbranch_scc1 .LBB0_1151
	s_mov_b32 s0, s33
	s_mov_b64 s[16:17], -1
	v_mov_b32_e32 v0, s0
	ds_read2_b32 v[2:3], v0 offset1:1
	s_waitcnt lgkmcnt(0)
	v_readfirstlane_b32 s0, v2
	v_readfirstlane_b32 s1, v3
	s_add_u32 s0, s0, s54
	s_addc_u32 s1, s1, 0
	s_add_u32 s14, s0, 0x100000
	s_addc_u32 s15, s1, 0
	s_cmp_lt_i32 s24, 2
	s_cbranch_scc1 .LBB0_1178
	s_cmp_lt_i32 s24, 3
	s_cbranch_scc1 .LBB0_1175
	s_cmp_lg_u32 s24, 3
	s_cbranch_scc0 .LBB0_1172
	s_cmp_gt_u32 s24, 7
	s_cbranch_scc0 .LBB0_1169
	s_cmp_lt_i32 s24, 9
	s_cbranch_scc1 .LBB0_1166
	s_cmp_lt_i32 s24, 10
	s_mov_b64 s[10:11], -1
	s_cbranch_scc1 .LBB0_1164
	s_cmp_lg_u32 s24, 10
	s_mov_b64 s[8:9], -1
	s_cbranch_scc0 .LBB0_1161
	v_readlane_b32 s0, v254, 0
	s_add_i32 s94, s24, -11
	s_mov_b64 s[8:9], 0
	v_mov_b32_e32 v0, s0
	ds_read2_b32 v[2:3], v0 offset1:1
	s_waitcnt lgkmcnt(0)
	v_readfirstlane_b32 s0, v2
	v_readfirstlane_b32 s1, v3
	s_add_u32 s6, s0, s4
	s_addc_u32 s7, s1, s5
	s_lshl_b64 s[0:1], s[94:95], 21
	s_add_u32 s6, s6, s0
	s_addc_u32 s7, s7, s1
	s_lshl_b64 s[0:1], s[94:95], 20
	s_add_u32 s0, s14, s0
	s_addc_u32 s1, s15, s1
	s_add_u32 s0, s0, 0x3280000
	s_addc_u32 s1, s1, 0

.LBB0_1309:
	s_lshl_b32 s0, 1, s13
	s_and_b32 s0, s0, 0x1df0
	s_cmp_eq_u32 s0, 0
	s_cbranch_scc1 .LBB0_1308
	s_mov_b32 s0, s33
	s_mov_b64 s[16:17], -1
	v_mov_b32_e32 v0, s0
	ds_read2_b32 v[2:3], v0 offset1:1
	s_waitcnt lgkmcnt(0)
	v_readfirstlane_b32 s0, v2
	v_readfirstlane_b32 s1, v3
	s_add_u32 s0, s0, s54
	s_addc_u32 s1, s1, 0
	s_add_u32 s14, s0, 0x100000
	s_addc_u32 s15, s1, 0
	s_cmp_lt_i32 s13, 2
	s_cbranch_scc1 .LBB0_1335
	s_cmp_lt_i32 s13, 3
	s_cbranch_scc1 .LBB0_1332
	s_cmp_lg_u32 s13, 3
	s_cbranch_scc0 .LBB0_1329
	s_cmp_gt_u32 s13, 7
	s_cbranch_scc0 .LBB0_1326
	s_cmp_lt_i32 s13, 9
	s_cbranch_scc1 .LBB0_1323
	s_cmp_lt_i32 s13, 10
	s_mov_b64 s[10:11], -1
	s_cbranch_scc1 .LBB0_1321
	s_cmp_lg_u32 s13, 10
	s_mov_b64 s[8:9], -1
	s_cbranch_scc0 .LBB0_1318
	v_readlane_b32 s0, v254, 0
	s_add_i32 s94, s13, -11
	s_mov_b64 s[8:9], 0
	v_mov_b32_e32 v0, s0
	ds_read2_b32 v[2:3], v0 offset1:1
	s_waitcnt lgkmcnt(0)
	v_readfirstlane_b32 s0, v2
	v_readfirstlane_b32 s1, v3
	s_add_u32 s6, s0, s4
	s_addc_u32 s7, s1, s5
	s_lshl_b64 s[0:1], s[94:95], 21
	s_add_u32 s6, s6, s0
	s_addc_u32 s7, s7, s1
	s_lshl_b64 s[0:1], s[94:95], 20
	s_add_u32 s0, s14, s0
	s_addc_u32 s1, s15, s1
	s_add_u32 s0, s0, 0x3280000
	s_addc_u32 s1, s1, 0
